# v26 + mla_norm rope table read from LDS (removes per-row vmcnt(0) drain) + cache_convert K-part: four tile loads issued together, single wait
# speedup vs baseline: 1.0289x; 1.0072x over previous
.LBB0_259:
	s_mov_b32 s98, 0x20000
	s_mov_b32 s99, 0x22000
	s_cmp_eq_u32 s56, 0
	s_cbranch_scc1 .Lrope_fill
	s_cmp_eq_u32 s56, 21
	s_cbranch_scc1 .Lrope_fill
	s_cmp_eq_u32 s56, 30
	s_cbranch_scc0 .Lrope_nofill

.LBB0_265:
	v_ashrrev_i32_e32 v19, 31, v18
	v_lshl_add_u64 v[2:3], v[18:19], 4, s[10:11]
	global_load_dwordx4 v[2:5], v[2:3], off
	v_add_u32_e32 v6, s21, v18
	v_cmp_gt_i32_e64 s[4:5], s2, v6
	v_mov_b32_e32 v11, 0
	v_ashrrev_i32_e32 v7, 31, v6
	v_mov_b32_e32 v17, 0
	v_mov_b32_e32 v16, 0
	s_and_saveexec_b64 s[0:1], s[4:5]
	s_cbranch_execz .LBB0_267
	v_lshl_add_u64 v[8:9], v[6:7], 4, s[10:11]
	global_load_dwordx4 v[26:29], v[8:9], off
.LBB0_267:
	s_or_b64 exec, exec, s[0:1]
	v_add_u32_e32 v14, s25, v18
	v_cmp_gt_i32_e64 s[0:1], s2, v14
	v_ashrrev_i32_e32 v15, 31, v14
	v_mov_b32_e32 v10, 0
	s_and_saveexec_b64 s[18:19], s[0:1]
	s_cbranch_execz .LBB0_269
	v_lshl_add_u64 v[8:9], v[14:15], 4, s[10:11]
	global_load_dwordx4 v[30:33], v[8:9], off
.LBB0_269:
	s_or_b64 exec, exec, s[18:19]
	v_add_u32_e32 v12, s28, v18
	v_cmp_gt_i32_e32 vcc, s2, v12
	v_mov_b32_e32 v9, 0
	v_ashrrev_i32_e32 v13, 31, v12
	v_mov_b32_e32 v8, 0
	s_and_saveexec_b64 s[18:19], vcc
	s_cbranch_execz .LBB0_271
	v_lshl_add_u64 v[8:9], v[12:13], 4, s[10:11]
	global_load_dwordx4 v[34:37], v[8:9], off
.LBB0_271:
	s_or_b64 exec, exec, s[18:19]
	v_sub_u32_e32 v22, 0, v18
	v_max_i32_e32 v18, v18, v22
	v_mul_hi_u32 v22, v18, v21
	v_mul_lo_u32 v23, v22, s3
	v_sub_u32_e32 v18, v18, v23
	v_add_u32_e32 v23, 1, v22
	v_cmp_le_u32_e64 s[36:37], s3, v18
	s_waitcnt vmcnt(0)
	v_cvt_pk_bf16_f32 v2, v2, v3
	v_cvt_pk_bf16_f32 v3, v4, v5
	v_cvt_pk_bf16_f32 v16, v26, v27
	v_cvt_pk_bf16_f32 v17, v28, v29
	v_cvt_pk_bf16_f32 v10, v30, v31
	v_cvt_pk_bf16_f32 v11, v32, v33
	v_cvt_pk_bf16_f32 v8, v34, v35
	v_cvt_pk_bf16_f32 v9, v36, v37
	v_cndmask_b32_e64 v22, v22, v23, s[36:37]
	v_subrev_u32_e32 v23, s3, v18
	v_cndmask_b32_e64 v18, v18, v23, s[36:37]
	v_add_u32_e32 v23, 1, v22
	v_cmp_le_u32_e64 s[36:37], s3, v18
	s_nop 1
	v_cndmask_b32_e64 v18, v22, v23, s[36:37]
	v_xor_b32_e32 v18, v18, v19
	v_sub_u32_e32 v18, v18, v19
	v_ashrrev_i32_e32 v22, 9, v18
	v_mul_i32_i24_e32 v4, 0x1200, v22
	v_and_or_b32 v4, v18, s44, v4
	v_lshlrev_b32_e32 v19, s8, v18
	v_add_u32_e32 v4, 0x2000, v4
	v_ashrrev_i32_e32 v5, 31, v4
	v_lshlrev_b32_e32 v18, 2, v19
	v_lshlrev_b64 v[4:5], s20, v[4:5]
	v_sub_u32_e32 v18, v0, v18
	v_lshl_add_u64 v[4:5], v[4:5], 1, s[50:51]
	v_ashrrev_i32_e32 v19, 31, v18
	v_lshl_add_u64 v[4:5], v[18:19], 1, v[4:5]
	global_store_dwordx2 v[4:5], v[2:3], off
	s_and_saveexec_b64 s[18:19], s[4:5]
	s_cbranch_execz .LBB0_274
	v_sub_u32_e32 v2, 0, v6
	v_max_i32_e32 v2, v6, v2
	v_mul_hi_u32 v3, v2, v21
	v_mul_lo_u32 v4, v3, s3
	v_sub_u32_e32 v2, v2, v4
	v_add_u32_e32 v4, 1, v3
	v_cmp_le_u32_e64 s[4:5], s3, v2
	v_add_u32_e32 v5, s24, v0
	s_nop 0
	v_cndmask_b32_e64 v3, v3, v4, s[4:5]
	v_subrev_u32_e32 v4, s3, v2
	v_cndmask_b32_e64 v2, v2, v4, s[4:5]
	v_add_u32_e32 v4, 1, v3
	v_cmp_le_u32_e64 s[4:5], s3, v2
	s_nop 1
	v_cndmask_b32_e64 v2, v3, v4, s[4:5]
	v_xor_b32_e32 v2, v2, v7
	v_sub_u32_e32 v2, v2, v7
	v_ashrrev_i32_e32 v3, 9, v2
	v_mul_i32_i24_e32 v3, 0x1200, v3
	v_lshlrev_b32_e32 v4, s8, v2
	v_and_or_b32 v2, v2, s44, v3
	v_add_u32_e32 v2, 0x2000, v2
	v_ashrrev_i32_e32 v3, 31, v2
	v_lshlrev_b32_e32 v4, 2, v4
	v_lshlrev_b64 v[2:3], s20, v[2:3]
	v_sub_u32_e32 v4, v5, v4
	v_lshl_add_u64 v[2:3], v[2:3], 1, s[50:51]
	v_ashrrev_i32_e32 v5, 31, v4
	v_lshl_add_u64 v[2:3], v[4:5], 1, v[2:3]
	global_store_dwordx2 v[2:3], v[16:17], off
	s_or_b64 exec, exec, s[18:19]
	s_and_saveexec_b64 s[4:5], s[0:1]
	s_cbranch_execnz .LBB0_275

.LBB0_477:
	v_add_u32_e32 v29, 1, v34
	v_cmp_lt_i32_e32 vcc, v29, v23
	v_mov_b64_e32 v[14:15], s[94:95]
	s_movk_i32 s2, 0x640
	v_cndmask_b32_e32 v16, v34, v29, vcc
	v_mad_i64_i32 v[70:71], s[2:3], v16, s2, v[14:15]
	v_mov_b32_e32 v33, v1
	v_mov_b32_e32 v49, v1
	v_lshl_add_u64 v[14:15], v[70:71], 0, v[0:1]
	v_lshl_add_u64 v[58:59], v[70:71], 0, v[32:33]
	v_lshl_add_u64 v[70:71], v[70:71], 0, v[48:49]
	global_load_dwordx4 v[14:17], v[14:15], off
	s_nop 0
	global_load_dwordx2 v[58:59], v[58:59], off offset:1024
	s_movk_i32 s2, 0x2000
	global_load_ushort v33, v[70:71], off offset:1536
	v_cmp_ge_i32_e64 s[38:39], v29, v23
	v_cmp_gt_i32_e64 s[40:41], s2, v34
	v_cmp_lt_i32_e32 vcc, s55, v34
	v_mov_b32_e32 v39, 0
	s_and_saveexec_b64 s[14:15], vcc
	v_add_u32_e32 v35, 0xffffe000, v34
	v_lshrrev_b32_e32 v35, 12, v35
	v_and_b32_e32 v39, 0xfff, v34
	v_mul_u32_u24_e32 v34, 0x1200, v35
	s_movk_i32 s2, 0x2200
	v_add3_u32 v34, v39, v34, s2
	s_or_b64 exec, exec, s[14:15]
	v_mul_f32_e32 v70, v21, v21
	v_pk_fma_f32 v[70:71], v[20:21], v[20:21], v[70:71] op_sel_hi:[1,1,0]
	v_mul_f32_e32 v72, v53, v53
	v_pk_fma_f32 v[70:71], v[52:53], v[52:53], v[70:71]
	v_pk_mul_f32 v[76:77], v[18:19], v[18:19]
	v_pk_add_f32 v[70:71], v[72:73], v[70:71] op_sel_hi:[0,1]
	v_pk_mul_f32 v[72:73], v[54:55], v[54:55]
	v_pk_fma_f32 v[70:71], v[54:55], v[54:55], v[70:71]
	v_pk_mul_f32 v[74:75], v[56:57], v[56:57]
	v_pk_mul_f32 v[78:79], v[50:51], v[50:51]
	v_mov_b32_e32 v72, v77
	v_mov_b32_e32 v77, v70
	v_pk_add_f32 v[70:71], v[72:73], v[76:77]
	v_mov_b32_e32 v72, v78
	v_mov_b32_e32 v73, v74
	v_pk_add_f32 v[70:71], v[72:73], v[70:71]
	v_mov_b32_e32 v74, v79
	v_pk_add_f32 v[70:71], v[74:75], v[70:71]
	ds_bpermute_b32 v73, v65, v71
	ds_bpermute_b32 v72, v65, v70
	s_mov_b32 s2, 0x3b800000
	s_mov_b32 s3, 0x3b000000
	s_waitcnt lgkmcnt(0)
	v_pk_add_f32 v[70:71], v[70:71], v[72:73]
	ds_bpermute_b32 v73, v66, v71
	ds_bpermute_b32 v72, v66, v70
	s_waitcnt lgkmcnt(0)
	v_pk_add_f32 v[70:71], v[70:71], v[72:73]
	ds_bpermute_b32 v73, v67, v71
	ds_bpermute_b32 v72, v67, v70
	s_waitcnt lgkmcnt(0)
	v_pk_add_f32 v[70:71], v[70:71], v[72:73]
	ds_bpermute_b32 v73, v68, v71
	ds_bpermute_b32 v72, v68, v70
	s_waitcnt lgkmcnt(0)
	v_pk_add_f32 v[70:71], v[70:71], v[72:73]
	ds_bpermute_b32 v73, v69, v71
	ds_bpermute_b32 v72, v69, v70
	s_waitcnt lgkmcnt(0)
	v_pk_add_f32 v[70:71], v[70:71], v[72:73]
	ds_bpermute_b32 v73, v63, v71
	ds_bpermute_b32 v72, v63, v70
	s_waitcnt lgkmcnt(0)
	v_pk_add_f32 v[70:71], v[70:71], v[72:73]
	s_nop 0
	v_pk_fma_f32 v[70:71], v[70:71], s[2:3], v[146:147] op_sel_hi:[1,1,0]
	v_lshl_add_u64 v[72:73], v[44:45], 0, v[30:31]
	v_mul_f32_e32 v35, 0x4b800000, v71
	v_cmp_gt_f32_e32 vcc, s54, v71
	v_mul_f32_e32 v49, 0x4b800000, v70
	s_brev_b32 s2, 40
	v_cndmask_b32_e32 v35, v71, v35, vcc
	v_rsq_f32_e32 v35, v35
	s_nop 0
	v_mul_f32_e32 v71, 0x45800000, v35
	v_cndmask_b32_e32 v74, v35, v71, vcc
	v_pk_mul_f32 v[20:21], v[20:21], v[74:75] op_sel_hi:[1,0]
	v_pk_mul_f32 v[52:53], v[52:53], v[74:75] op_sel_hi:[1,0]
	v_pk_mul_f32 v[20:21], v[6:7], v[20:21]
	v_cmp_gt_f32_e32 vcc, s54, v70
	v_pk_mul_f32 v[54:55], v[54:55], v[74:75] op_sel_hi:[1,0]
	v_pk_mul_f32 v[56:57], v[56:57], v[74:75] op_sel_hi:[1,0]
	v_pk_mul_f32 v[74:75], v[8:9], v[52:53]
	v_cvt_pk_bf16_f32 v52, v20, v21
	v_cndmask_b32_e32 v20, v70, v49, vcc
	v_rsq_f32_e32 v35, v20
	v_pk_mul_f32 v[54:55], v[2:3], v[54:55]
	v_pk_mul_f32 v[56:57], v[4:5], v[56:57]
	v_add_co_u32_e64 v20, s[42:43], s2, v72
	v_cvt_pk_bf16_f32 v53, v74, v75
	v_cvt_pk_bf16_f32 v54, v54, v55
	v_cvt_pk_bf16_f32 v55, v56, v57
	v_addc_co_u32_e64 v21, s[42:43], 0, v73, s[42:43]
	global_store_dwordx4 v[20:21], v[52:55], off
	v_mul_f32_e32 v20, 0x45800000, v35
	v_cndmask_b32_e32 v20, v35, v20, vcc
	v_pk_mul_f32 v[18:19], v[18:19], v[20:21] op_sel_hi:[1,0]
	v_pk_mul_f32 v[20:21], v[50:51], v[20:21] op_sel_hi:[1,0]
	v_ashrrev_i32_e32 v35, 31, v34
	v_pk_mul_f32 v[18:19], v[10:11], v[18:19]
	v_pk_mul_f32 v[20:21], v[12:13], v[20:21]
	v_lshlrev_b64 v[52:53], 9, v[34:35]
	v_cvt_pk_bf16_f32 v50, v18, v19
	v_cvt_pk_bf16_f32 v51, v20, v21
	v_lshl_add_u64 v[52:53], v[24:25], 0, v[52:53]
	global_store_dwordx2 v[52:53], v[50:51], off
	s_and_saveexec_b64 s[14:15], s[40:41]
	s_cbranch_execz .LBB0_481
	v_lshl_add_u64 v[50:51], v[46:47], 0, v[30:31]
	v_add_co_u32_e32 v50, vcc, 0x12000000, v50
	s_nop 1
	v_addc_co_u32_e32 v51, vcc, 0, v51, vcc
	global_store_dwordx4 v[50:51], v[18:21], off

.LBB0_486:
	s_andn2_saveexec_b64 s[14:15], s[14:15]
	s_cbranch_execz .LBB0_476
	s_waitcnt lgkmcnt(0)
	v_and_b32_e32 v20, 63, v39
	v_lshrrev_b32_e32 v21, 6, v39
	v_cndmask_b32_e64 v20, v20, v21, s[36:37]
	v_lshlrev_b32_e32 v21, 2, v38
	v_lshl_or_b32 v20, v20, 6, v21
	v_add_u32_e32 v20, s99, v20
	ds_read_b64 v[50:51], v20
	s_waitcnt lgkmcnt(0)
	v_mul_f32_e32 v21, v51, v18
	v_mul_f32_e32 v20, v51, v19
	v_fma_f32 v19, v50, v19, -v21
	v_fmac_f32_e32 v20, v50, v18
	ds_bpermute_b32 v21, v63, v19
	ds_bpermute_b32 v18, v63, v20
	s_and_saveexec_b64 s[16:17], s[10:11]
	s_cbranch_execz .LBB0_475
	v_lshlrev_b64 v[34:35], 6, v[34:35]
	s_waitcnt lgkmcnt(1)
	v_cvt_pk_bf16_f32 v19, v19, v21
	v_lshl_add_u64 v[34:35], v[40:41], 0, v[34:35]
	s_waitcnt lgkmcnt(0)
	v_cvt_pk_bf16_f32 v18, v20, v18
	global_store_dword v[34:35], v19, off
	global_store_dword v[34:35], v18, off offset:16
	s_branch .LBB0_475
